# cmp pass B importance shuffles via DPP quad_perm instead of ds_bpermute round trips (on top of v26)
# speedup vs baseline: 1.0062x; 1.0051x over previous
; #define LAS __attribute__((address_space(3)))
; __device__ __forceinline__ void attn_fast(const Ptrs& P, LAS unsigned char* lds, int G, int bid) {
;     ...
;                         for (int jj = 0; jj < 4; ++jj) s[ct][kt][jj] = __builtin_amdgcn_exp2f(__builtin_fmaf(s[ct][kt][jj], SC, -m[ct])) * il[ct];
;                         float s4 = (s[ct][kt][0] + s[ct][kt][1]) + (s[ct][kt][2] + s[ct][kt][3]), s3 = s[ct][kt][3];
;                         s4 += __shfl_xor(s4, 1); s4 += __shfl_xor(s4, 2); s3 += __shfl_xor(s3, 1); s3 += __shfl_xor(s3, 2);
;                         if (hh == 0) { LAS float* ip = IMP + (4 * ct + qi) * 132 + 16 * T + 4 * kt + fq;
;                             __hip_atomic_fetch_add(ip, s4, __ATOMIC_RELAXED, __HIP_MEMORY_SCOPE_WORKGROUP);
;                             __hip_atomic_fetch_add(ip + 1, s3, __ATOMIC_RELAXED, __HIP_MEMORY_SCOPE_WORKGROUP); }
.LBB0_547:
	v_fma_f32 v2, v130, s89, -v136
	v_exp_f32_e32 v141, v2
	v_fma_f32 v2, v131, s89, -v136
	v_exp_f32_e32 v130, v2
	v_fma_f32 v2, v132, s89, -v136
	v_exp_f32_e32 v131, v2
	v_fma_f32 v2, v133, s89, -v136
	v_exp_f32_e32 v142, v2
	v_pk_mul_f32 v[130:131], v[4:5], v[130:131]
	s_nop 0
	v_fma_f32 v2, v4, v141, v130
	v_fma_f32 v132, v4, v142, v131
	v_add_f32_e32 v133, v2, v132
	v_mul_f32_e32 v2, v4, v142
	s_nop 0
	v_mov_b32_dpp v143, v133 quad_perm:[1,0,3,2] row_mask:0xf bank_mask:0xf
	v_mov_b32_dpp v132, v2 quad_perm:[1,0,3,2] row_mask:0xf bank_mask:0xf
	v_add_f32_e32 v133, v133, v143
	v_fmac_f32_e32 v132, v4, v142
	s_nop 0
	v_mov_b32_dpp v143, v133 quad_perm:[2,3,0,1] row_mask:0xf bank_mask:0xf
	v_mov_b32_dpp v144, v132 quad_perm:[2,3,0,1] row_mask:0xf bank_mask:0xf
	v_add_u32_e32 v142, 0, v140
	s_and_saveexec_b64 s[52:53], s[10:11]
	s_cbranch_execz .LBB0_549
	v_add_u32_e32 v161, 0x18000, v142
	v_add_f32_e32 v133, v133, v143
	v_add_u32_e32 v162, 0x18004, v142
	v_add_f32_e32 v132, v132, v144
	ds_add_f32 v161, v133
	ds_add_f32 v162, v132
.LBB0_549:
	s_or_b64 exec, exec, s[52:53]
	v_fma_f32 v128, v128, s89, -v136
	v_fma_f32 v126, v126, s89, -v136
	v_fma_f32 v127, v127, s89, -v136
	v_exp_f32_e32 v132, v128
	v_fma_f32 v128, v129, s89, -v136
	v_exp_f32_e32 v126, v126
	v_exp_f32_e32 v127, v127
	v_exp_f32_e32 v133, v128
	v_pk_mul_f32 v[128:129], v[4:5], v[126:127]
	v_pk_mul_f32 v[126:127], v[4:5], v[132:133]
	v_add_f32_e32 v133, v128, v129
	v_add_f32_e32 v132, v126, v127
	v_add_f32_e32 v132, v133, v132
	s_nop 1
	v_mov_b32_dpp v133, v132 quad_perm:[1,0,3,2] row_mask:0xf bank_mask:0xf
	v_mov_b32_dpp v143, v127 quad_perm:[1,0,3,2] row_mask:0xf bank_mask:0xf
	v_add_f32_e32 v132, v132, v133
	v_add_f32_e32 v143, v127, v143
	s_nop 0
	v_mov_b32_dpp v133, v132 quad_perm:[2,3,0,1] row_mask:0xf bank_mask:0xf
	v_mov_b32_dpp v144, v143 quad_perm:[2,3,0,1] row_mask:0xf bank_mask:0xf
	s_and_saveexec_b64 s[52:53], s[10:11]
	s_cbranch_execz .LBB0_551
	v_add_u32_e32 v162, 0x18010, v142
	v_add_f32_e32 v132, v132, v133
	v_add_u32_e32 v161, 0x18014, v142
	v_add_f32_e32 v133, v143, v144
	ds_add_f32 v162, v132
	ds_add_f32 v161, v133
.LBB0_551:
	s_or_b64 exec, exec, s[52:53]
	v_fma_f32 v122, v122, s89, -v136
	v_exp_f32_e32 v144, v122
	v_fma_f32 v122, v123, s89, -v136
	v_fma_f32 v123, v124, s89, -v136
	v_exp_f32_e32 v122, v122
	v_exp_f32_e32 v123, v123
	v_fma_f32 v124, v125, s89, -v136
	v_exp_f32_e32 v133, v124
	v_pk_mul_f32 v[122:123], v[4:5], v[122:123]
	s_nop 0
	v_fma_f32 v124, v4, v144, v122
	v_fma_f32 v125, v4, v133, v123
	v_add_f32_e32 v125, v124, v125
	v_mul_f32_e32 v143, v4, v133
	s_nop 0
	v_mov_b32_dpp v132, v125 quad_perm:[1,0,3,2] row_mask:0xf bank_mask:0xf
	v_mov_b32_dpp v124, v143 quad_perm:[1,0,3,2] row_mask:0xf bank_mask:0xf
	v_add_f32_e32 v125, v125, v132
	v_fmac_f32_e32 v124, v4, v133
	s_nop 0
	v_mov_b32_dpp v132, v125 quad_perm:[2,3,0,1] row_mask:0xf bank_mask:0xf
	v_mov_b32_dpp v133, v124 quad_perm:[2,3,0,1] row_mask:0xf bank_mask:0xf
	s_and_saveexec_b64 s[52:53], s[10:11]
	s_cbranch_execz .LBB0_553
	v_add_u32_e32 v162, 0x18020, v142
	v_add_f32_e32 v125, v125, v132
	v_add_u32_e32 v161, 0x18024, v142
	v_add_f32_e32 v124, v124, v133
	ds_add_f32 v162, v125
	ds_add_f32 v161, v124
.LBB0_553:
	s_or_b64 exec, exec, s[52:53]
	v_fma_f32 v120, v120, s89, -v136
	v_fma_f32 v118, v118, s89, -v136
	v_fma_f32 v119, v119, s89, -v136
	v_exp_f32_e32 v124, v120
	v_fma_f32 v120, v121, s89, -v136
	v_exp_f32_e32 v118, v118
	v_exp_f32_e32 v119, v119
	v_exp_f32_e32 v125, v120
	v_pk_mul_f32 v[120:121], v[4:5], v[118:119]
	v_pk_mul_f32 v[118:119], v[4:5], v[124:125]
	v_add_f32_e32 v125, v120, v121
	v_add_f32_e32 v124, v118, v119
	v_add_f32_e32 v124, v125, v124
	s_nop 1
	v_mov_b32_dpp v125, v124 quad_perm:[1,0,3,2] row_mask:0xf bank_mask:0xf
	v_mov_b32_dpp v132, v119 quad_perm:[1,0,3,2] row_mask:0xf bank_mask:0xf
	v_add_f32_e32 v124, v124, v125
	v_add_f32_e32 v132, v119, v132
	s_nop 0
	v_mov_b32_dpp v125, v124 quad_perm:[2,3,0,1] row_mask:0xf bank_mask:0xf
	v_mov_b32_dpp v133, v132 quad_perm:[2,3,0,1] row_mask:0xf bank_mask:0xf
	s_and_saveexec_b64 s[52:53], s[10:11]
	s_cbranch_execz .LBB0_555
	v_add_u32_e32 v162, 0x18030, v142
	v_add_f32_e32 v124, v124, v125
	v_add_u32_e32 v161, 0x18034, v142
	v_add_f32_e32 v125, v132, v133
	ds_add_f32 v162, v124
	ds_add_f32 v161, v125

; #define LAS __attribute__((address_space(3)))
; __device__ __forceinline__ void attn_fast(const Ptrs& P, LAS unsigned char* lds, int G, int bid) {
;     ...
;                         for (int jj = 0; jj < 4; ++jj) s[ct][kt][jj] = __builtin_amdgcn_exp2f(__builtin_fmaf(s[ct][kt][jj], SC, -m[ct])) * il[ct];
;                         float s4 = (s[ct][kt][0] + s[ct][kt][1]) + (s[ct][kt][2] + s[ct][kt][3]), s3 = s[ct][kt][3];
;                         s4 += __shfl_xor(s4, 1); s4 += __shfl_xor(s4, 2); s3 += __shfl_xor(s3, 1); s3 += __shfl_xor(s3, 2);
;                         if (hh == 0) { LAS float* ip = IMP + (4 * ct + qi) * 132 + 16 * T + 4 * kt + fq;
;                             __hip_atomic_fetch_add(ip, s4, __ATOMIC_RELAXED, __HIP_MEMORY_SCOPE_WORKGROUP);
;                             __hip_atomic_fetch_add(ip + 1, s3, __ATOMIC_RELAXED, __HIP_MEMORY_SCOPE_WORKGROUP); }
.LBB0_557:
	v_fma_f32 v114, v114, s89, -v137
	v_exp_f32_e32 v147, v114
	v_fma_f32 v114, v115, s89, -v137
	v_fma_f32 v115, v116, s89, -v137
	v_exp_f32_e32 v114, v114
	v_exp_f32_e32 v115, v115
	v_fma_f32 v116, v117, s89, -v137
	v_exp_f32_e32 v125, v116
	v_pk_mul_f32 v[114:115], v[134:135], v[114:115]
	s_nop 0
	v_fma_f32 v116, v134, v147, v114
	v_fma_f32 v117, v134, v125, v115
	v_add_f32_e32 v117, v116, v117
	v_mul_f32_e32 v145, v134, v125
	s_nop 0
	v_mov_b32_dpp v124, v117 quad_perm:[1,0,3,2] row_mask:0xf bank_mask:0xf
	v_mov_b32_dpp v116, v145 quad_perm:[1,0,3,2] row_mask:0xf bank_mask:0xf
	v_add_f32_e32 v117, v117, v124
	v_fmac_f32_e32 v116, v134, v125
	s_nop 0
	v_mov_b32_dpp v124, v117 quad_perm:[2,3,0,1] row_mask:0xf bank_mask:0xf
	v_mov_b32_dpp v125, v116 quad_perm:[2,3,0,1] row_mask:0xf bank_mask:0xf
	s_and_saveexec_b64 s[6:7], s[10:11]
	s_cbranch_execz .LBB0_559
	v_add_f32_e32 v117, v117, v124
	v_add_u32_e32 v124, 0x18840, v142
	v_add_u32_e32 v132, 0x18844, v142
	v_add_f32_e32 v116, v116, v125
	ds_add_f32 v124, v117
	ds_add_f32 v132, v116
.LBB0_559:
	s_or_b64 exec, exec, s[6:7]
	v_fma_f32 v110, v110, s89, -v137
	v_fma_f32 v111, v111, s89, -v137
	v_fma_f32 v112, v112, s89, -v137
	v_fma_f32 v113, v113, s89, -v137
	v_exp_f32_e32 v110, v110
	v_exp_f32_e32 v111, v111
	v_exp_f32_e32 v112, v112
	v_exp_f32_e32 v113, v113
	v_pk_mul_f32 v[132:133], v[134:135], v[110:111]
	v_pk_mul_f32 v[110:111], v[134:135], v[112:113]
	s_nop 0
	v_add_f32_e32 v112, v110, v111
	v_add_f32_e32 v113, v132, v133
	v_add_f32_e32 v112, v113, v112
	s_nop 1
	v_mov_b32_dpp v113, v112 quad_perm:[1,0,3,2] row_mask:0xf bank_mask:0xf
	v_mov_b32_dpp v116, v111 quad_perm:[1,0,3,2] row_mask:0xf bank_mask:0xf
	v_add_f32_e32 v112, v112, v113
	v_add_f32_e32 v116, v111, v116
	s_nop 0
	v_mov_b32_dpp v113, v112 quad_perm:[2,3,0,1] row_mask:0xf bank_mask:0xf
	v_mov_b32_dpp v117, v116 quad_perm:[2,3,0,1] row_mask:0xf bank_mask:0xf
	s_and_saveexec_b64 s[6:7], s[10:11]
	s_cbranch_execz .LBB0_561
	v_add_u32_e32 v125, 0x18850, v142
	v_add_f32_e32 v112, v112, v113
	v_add_u32_e32 v124, 0x18854, v142
	v_add_f32_e32 v113, v116, v117
	ds_add_f32 v125, v112
	ds_add_f32 v124, v113
.LBB0_561:
	s_or_b64 exec, exec, s[6:7]
	v_fma_f32 v107, v107, s89, -v137
	v_exp_f32_e32 v112, v107
	v_fma_f32 v107, v108, s89, -v137
	v_fma_f32 v106, v106, s89, -v137
	v_exp_f32_e32 v113, v107
	v_fma_f32 v107, v109, s89, -v137
	v_exp_f32_e32 v106, v106
	v_exp_f32_e32 v116, v107
	v_pk_mul_f32 v[112:113], v[134:135], v[112:113]
	v_mul_f32_e32 v146, v134, v116
	v_fma_f32 v107, v134, v106, v112
	v_fma_f32 v108, v134, v116, v113
	v_add_f32_e32 v108, v107, v108
	s_nop 1
	v_mov_b32_dpp v109, v108 quad_perm:[1,0,3,2] row_mask:0xf bank_mask:0xf
	v_mov_b32_dpp v107, v146 quad_perm:[1,0,3,2] row_mask:0xf bank_mask:0xf
	v_add_f32_e32 v108, v108, v109
	v_fmac_f32_e32 v107, v134, v116
	s_nop 0
	v_mov_b32_dpp v109, v108 quad_perm:[2,3,0,1] row_mask:0xf bank_mask:0xf
	v_mov_b32_dpp v116, v107 quad_perm:[2,3,0,1] row_mask:0xf bank_mask:0xf
	s_and_saveexec_b64 s[6:7], s[10:11]
	s_cbranch_execz .LBB0_563
	v_add_u32_e32 v124, 0x18860, v142
	v_add_f32_e32 v108, v108, v109
	v_add_u32_e32 v117, 0x18864, v142
	v_add_f32_e32 v107, v107, v116
	ds_add_f32 v124, v108
	ds_add_f32 v117, v107
.LBB0_563:
	s_or_b64 exec, exec, s[6:7]
	v_fma_f32 v102, v102, s89, -v137
	v_fma_f32 v103, v103, s89, -v137
	v_fma_f32 v104, v104, s89, -v137
	v_fma_f32 v105, v105, s89, -v137
	v_exp_f32_e32 v102, v102
	v_exp_f32_e32 v103, v103
	v_exp_f32_e32 v104, v104
	v_exp_f32_e32 v105, v105
	v_pk_mul_f32 v[124:125], v[134:135], v[102:103]
	s_nop 0
	v_add_f32_e32 v103, v124, v125
	v_pk_mul_f32 v[116:117], v[134:135], v[104:105]
	s_nop 1
	v_mov_b32_dpp v104, v117 quad_perm:[1,0,3,2] row_mask:0xf bank_mask:0xf
	v_add_f32_e32 v102, v116, v117
	v_add_f32_e32 v102, v103, v102
	s_nop 1
	v_mov_b32_dpp v103, v102 quad_perm:[1,0,3,2] row_mask:0xf bank_mask:0xf
	v_add_f32_e32 v104, v117, v104
	s_nop 1
	v_mov_b32_dpp v105, v104 quad_perm:[2,3,0,1] row_mask:0xf bank_mask:0xf
	v_add_f32_e32 v102, v102, v103
	s_nop 1
	v_mov_b32_dpp v103, v102 quad_perm:[2,3,0,1] row_mask:0xf bank_mask:0xf
	s_and_saveexec_b64 s[6:7], s[10:11]
	s_cbranch_execz .LBB0_565
	v_add_u32_e32 v108, 0x18870, v142
	v_add_f32_e32 v102, v102, v103
	v_add_u32_e32 v107, 0x18874, v142
	v_add_f32_e32 v103, v104, v105
	ds_add_f32 v108, v102
	ds_add_f32 v107, v103
